# ride-along conv_w prologue: all 16 first-tile loads issued before the first wait (fresh regs for the last 5), call-start vmcnt(0) dropped
# speedup vs baseline: 1.0066x; 1.0066x over previous
;     ...
;     const int nkt = K / 64, ntiles = (Ntot / 128) * nkt;
;     float v[16];
;     ...
;     const int cstride = nwg ? nwg : (int)gridDim.x; bid -= wg0;
;     if (bid < 0) return;
;     if (bid < ntiles) CONVW_LOAD(bid);
; __global__ void __launch_bounds__(512, 2) fwd_mega(Params p) {
;     ...
;                     if (ck == 3 && ci >= 3 && ci <= 5) continue;
;                     conv_w(src, ldsrc, coloff, nvalid, Ntot, K, dst, inter, lds);
.LBB0_839:
	s_add_i32 s30, s2, -3
	s_cmp_lt_u32 s30, 3
	s_cselect_b64 s[30:31], -1, 0
	s_and_b64 s[30:31], s[6:7], s[30:31]
	s_and_b64 vcc, exec, s[30:31]
	s_cbranch_vccnz .LBB0_802
	s_nop 0
	v_mov_b32_e32 v11, v192
	s_mov_b32 s70, s52
	s_lshr_b32 s30, s55, 6
	s_mul_i32 s31, s30, s57
	s_cmp_gt_i32 s70, -1
	s_cselect_b64 s[68:69], -1, 0
	s_cmp_lt_i32 s70, s31
	s_cselect_b64 s[72:73], -1, 0
	s_and_b64 s[68:69], s[68:69], s[72:73]
	s_andn2_b64 vcc, exec, s[68:69]
	s_cbranch_vccnz .LBB0_802
	v_cvt_f32_u32_e32 v0, s30
	s_and_b32 s57, s70, 0xffff
	v_cvt_f32_u32_e32 v1, s57
	v_and_b32_e32 v20, 0x7f, v11
	v_rcp_iflag_f32_e32 v36, v0
	v_ashrrev_i32_e32 v62, 7, v11
	v_add_u32_e32 v23, 0x200, v11
	v_ashrrev_i32_e32 v61, 7, v23
	v_mul_f32_e32 v2, v1, v36
	v_trunc_f32_e32 v2, v2
	v_cvt_u32_f32_e32 v3, v2
	v_fma_f32 v1, -v2, v0, v1
	v_cmp_ge_f32_e64 s[68:69], |v1|, v0
	s_cmp_lg_u64 s[68:69], 0
	v_readfirstlane_b32 s57, v3
	s_addc_u32 s59, s57, 0
	s_and_b32 s68, s59, 0xffff
	s_add_i32 s57, s54, -1
	s_mul_i32 s59, s59, s30
	v_lshl_or_b32 v10, s68, 7, v20
	s_sub_i32 s59, s70, s59
	v_min_u32_e32 v0, s57, v10
	s_lshl_b32 s59, s59, 6
	v_lshlrev_b32_e32 v32, 2, v0
	s_and_b32 s59, s59, 0xffc0
	v_lshl_add_u64 v[0:1], s[4:5], 0, v[32:33]
	s_lshl_b64 s[26:27], s[26:27], 2
	v_lshl_add_u64 v[8:9], v[0:1], 0, s[26:27]
	v_add_u32_e32 v0, s59, v62
	v_add_u32_e32 v25, 0x400, v11
	v_mul_lo_u32 v32, v0, s56
	v_add_u32_e32 v2, s59, v61
	v_ashrrev_i32_e32 v60, 7, v25
	v_add_u32_e32 v27, 0x600, v11
	v_lshl_add_u64 v[0:1], v[32:33], 2, v[8:9]
	v_mul_lo_u32 v32, v2, s56
	v_add_u32_e32 v4, s59, v60
	v_ashrrev_i32_e32 v59, 7, v27
	v_add_u32_e32 v29, 0x800, v11
	v_lshl_add_u64 v[2:3], v[32:33], 2, v[8:9]
	v_mul_lo_u32 v32, v4, s56
	v_add_u32_e32 v6, s59, v59
	v_ashrrev_i32_e32 v58, 7, v29
	v_add_u32_e32 v31, 0xa00, v11
	v_lshl_add_u64 v[4:5], v[32:33], 2, v[8:9]
	v_mul_lo_u32 v32, v6, s56
	v_add_u32_e32 v12, s59, v58
	v_ashrrev_i32_e32 v57, 7, v31
	v_add_u32_e32 v35, 0xc00, v11
	v_lshl_add_u64 v[6:7], v[32:33], 2, v[8:9]
	v_mul_lo_u32 v32, v12, s56
	v_add_u32_e32 v14, s59, v57
	v_ashrrev_i32_e32 v56, 7, v35
	v_add_u32_e32 v37, 0xe00, v11
	v_lshl_add_u64 v[12:13], v[32:33], 2, v[8:9]
	v_mul_lo_u32 v32, v14, s56
	v_add_u32_e32 v16, s59, v56
	v_ashrrev_i32_e32 v55, 7, v37
	v_lshl_add_u64 v[14:15], v[32:33], 2, v[8:9]
	v_mul_lo_u32 v32, v16, s56
	v_add_u32_e32 v18, s59, v55
	v_lshl_add_u64 v[16:17], v[32:33], 2, v[8:9]
	v_mul_lo_u32 v32, v18, s56
	v_lshl_add_u64 v[18:19], v[32:33], 2, v[8:9]
	global_load_dword v21, v[0:1], off
	global_load_dword v22, v[2:3], off
	global_load_dword v24, v[4:5], off
	s_nop 0
	global_load_dword v6, v[6:7], off
	s_nop 0
	global_load_dword v7, v[12:13], off
	global_load_dword v26, v[14:15], off
	s_nop 0
	global_load_dword v16, v[16:17], off
	s_nop 0
	global_load_dword v17, v[18:19], off
	v_add_u32_e32 v0, 0x1000, v11
	v_ashrrev_i32_e32 v54, 7, v0
	v_add_u32_e32 v2, 0x1200, v11
	v_add_u32_e32 v0, s59, v54
	v_ashrrev_i32_e32 v53, 7, v2
	v_add_u32_e32 v4, 0x1400, v11
	v_mul_lo_u32 v32, v0, s56
	v_add_u32_e32 v2, s59, v53
	v_ashrrev_i32_e32 v52, 7, v4
	v_lshl_add_u64 v[0:1], v[32:33], 2, v[8:9]
	v_mul_lo_u32 v32, v2, s56
	v_add_u32_e32 v4, s59, v52
	v_lshl_add_u64 v[2:3], v[32:33], 2, v[8:9]
	v_mul_lo_u32 v32, v4, s56
	v_lshl_add_u64 v[4:5], v[32:33], 2, v[8:9]
	global_load_dword v28, v[0:1], off
	global_load_dword v30, v[2:3], off
	global_load_dword v34, v[4:5], off
	v_add_u32_e32 v0, 0x1600, v11
	v_add_u32_e32 v1, 0x1800, v11
	v_ashrrev_i32_e32 v51, 7, v0
	v_add_u32_e32 v2, 0x1a00, v11
	v_ashrrev_i32_e32 v50, 7, v1
	v_add_u32_e32 v0, s59, v51
	v_ashrrev_i32_e32 v49, 7, v2
	v_add_u32_e32 v1, s59, v50
	v_mul_lo_u32 v32, v0, s56
	v_lshl_add_u64 v[12:13], v[32:33], 2, v[8:9]
	v_mul_lo_u32 v32, v1, s56
	v_cmp_gt_u32_e32 vcc, s54, v10
	v_add_u32_e32 v10, s59, v49
	v_lshl_add_u64 v[14:15], v[32:33], 2, v[8:9]
	v_mul_lo_u32 v32, v10, s56
	v_add_u32_e32 v10, 0x1c00, v11
	v_ashrrev_i32_e32 v48, 7, v10
	v_add_u32_e32 v10, s59, v48
	v_mul_f32_e32 v36, 0x4f7ffffe, v36
	v_cvt_u32_f32_e32 v45, v36
	s_add_u32 s26, s4, s26
	s_addc_u32 s27, s5, s27
	v_ashrrev_i32_e32 v23, 5, v23
	v_ashrrev_i32_e32 v25, 5, v25
	v_ashrrev_i32_e32 v27, 5, v27
	v_ashrrev_i32_e32 v29, 5, v29
	v_ashrrev_i32_e32 v31, 5, v31
	v_ashrrev_i32_e32 v35, 5, v35
	v_ashrrev_i32_e32 v37, 5, v37
	v_mul_lo_u32 v65, v60, s82
	v_mul_lo_u32 v66, v59, s82
	v_mul_lo_u32 v67, v58, s82
	v_mul_lo_u32 v68, v57, s82
	v_mul_lo_u32 v69, v56, s82
	v_mul_lo_u32 v70, v55, s82
	v_mul_lo_u32 v71, v54, s82
	v_mul_lo_u32 v72, v53, s82
	v_mul_lo_u32 v73, v52, s82
	v_mul_lo_u32 v74, v51, s82
	v_mul_lo_u32 v75, v50, s82
	v_mul_lo_u32 v76, v49, s82
	v_mul_lo_u32 v77, v48, s82
	v_and_b32_e32 v40, 0x7f, v23
	v_and_b32_e32 v41, 0x7f, v25
	v_and_b32_e32 v42, 0x7f, v27
	v_and_b32_e32 v43, 0x7f, v29
	v_and_b32_e32 v44, 0x7f, v31
	v_and_b32_e32 v46, 0x7f, v35
	v_and_b32_e32 v63, 0x7f, v37
	v_lshl_add_u64 v[128:129], v[32:33], 2, v[8:9]
	v_mul_lo_u32 v32, v10, s56
	v_add_u32_e32 v10, 0x1e00, v11
	v_ashrrev_i32_e32 v47, 7, v10
	v_add_u32_e32 v10, s59, v47
	v_lshl_add_u64 v[130:131], v[32:33], 2, v[8:9]
	v_mul_lo_u32 v32, v10, s56
	v_lshl_add_u64 v[132:133], v[32:33], 2, v[8:9]
	global_load_dword v134, v[12:13], off
	global_load_dword v135, v[14:15], off
	global_load_dword v136, v[128:129], off
	global_load_dword v137, v[130:131], off
	global_load_dword v138, v[132:133], off
	s_waitcnt vmcnt(0)
;     ...
;     const int cstride = nwg ? nwg : (int)gridDim.x; bid -= wg0;
;     if (bid < 0) return;
;     if (bid < ntiles) CONVW_LOAD(bid);
;     for (int t = bid; t < ntiles; t += cstride) {
;         const int n0 = (t / nkt) * 128, k0 = (t % nkt) * 64;
; #pragma unroll
;         for (int it = 0; it < 16; ++it) { const int e = tid + 512 * it, kk = e >> 7, nn = e & 127; tile[kk * 129 + nn] = v[it]; }
	v_cndmask_b32_e32 v0, 0, v21, vcc
	v_ashrrev_i32_e32 v21, 5, v11
	v_and_b32_e32 v39, 0x7f, v21
	v_cndmask_b32_e32 v3, 0, v6, vcc
	v_cndmask_b32_e32 v4, 0, v7, vcc
	v_cndmask_b32_e32 v1, 0, v22, vcc
	v_cndmask_b32_e32 v6, 0, v16, vcc
	v_cndmask_b32_e32 v7, 0, v17, vcc
	v_lshlrev_b32_e32 v16, 1, v11
	s_lshl_b32 s59, s58, 7
	v_and_b32_e32 v16, 62, v16
	s_cmp_lt_i32 s58, 0
	v_lshlrev_b32_e32 v32, 1, v16
	s_cselect_b64 s[4:5], -1, 0
	v_mad_u32_u24 v38, v16, s82, 0
	v_lshl_add_u64 v[16:17], s[28:29], 0, v[32:33]
	v_readfirstlane_b32 s28, v45
	s_sub_i32 s29, 0, s30
	s_mul_i32 s29, s29, s28
	s_mul_hi_u32 s29, s28, s29
	v_lshl_add_u32 v19, v20, 2, 0
	v_mul_lo_u32 v11, v62, s82
	v_mul_lo_u32 v32, v61, s82
	v_mul_lo_u32 v78, v47, s82
	s_add_i32 s58, s28, s29
	s_lshl_b32 s28, s30, 6
	s_lshl_b32 s69, s34, 6
	v_cndmask_b32_e32 v2, 0, v24, vcc
	v_cndmask_b32_e32 v5, 0, v26, vcc
	v_cndmask_b32_e32 v8, 0, v28, vcc
	v_cndmask_b32_e32 v9, 0, v30, vcc
	v_cndmask_b32_e32 v10, 0, v34, vcc
	v_lshl_add_u32 v22, v21, 2, v38
	v_lshl_add_u32 v24, v23, 2, v38
	v_lshl_add_u32 v26, v25, 2, v38
	v_lshl_add_u32 v28, v27, 2, v38
	v_lshl_add_u32 v30, v29, 2, v38
	v_lshl_add_u32 v34, v31, 2, v38
	v_lshl_add_u32 v36, v35, 2, v38
	v_lshl_add_u32 v38, v37, 2, v38
	v_or_b32_e32 v39, s59, v39
	v_or_b32_e32 v40, s59, v40
	v_or_b32_e32 v41, s59, v41
	v_or_b32_e32 v42, s59, v42
	v_or_b32_e32 v43, s59, v43
	v_or_b32_e32 v44, s59, v44
	v_or_b32_e32 v45, s59, v46
	v_or_b32_e32 v46, s59, v63
	s_sub_i32 s59, 0, s28
	s_lshl_b32 s68, s70, 6
	v_add_u32_e32 v47, s69, v47
	v_add_u32_e32 v48, s69, v48
	v_add_u32_e32 v49, s69, v49
	v_add_u32_e32 v50, s69, v50
	v_add_u32_e32 v51, s69, v51
	v_add_u32_e32 v52, s69, v52
	v_add_u32_e32 v53, s69, v53
	v_add_u32_e32 v54, s69, v54
	v_add_u32_e32 v55, s69, v55
	v_add_u32_e32 v56, s69, v56
	v_add_u32_e32 v57, s69, v57
	v_add_u32_e32 v58, s69, v58
	v_add_u32_e32 v59, s69, v59
	v_add_u32_e32 v60, s69, v60
	v_add_u32_e32 v61, s69, v61
	v_add_u32_e32 v62, s69, v62
	v_add_u32_e32 v63, v19, v11
	v_add_u32_e32 v64, v19, v32
	v_add_u32_e32 v65, v19, v65
	v_add_u32_e32 v66, v19, v66
	v_add_u32_e32 v67, v19, v67
	v_add_u32_e32 v68, v19, v68
	v_add_u32_e32 v69, v19, v69
	v_add_u32_e32 v70, v19, v70
	v_add_u32_e32 v71, v19, v71
	v_add_u32_e32 v72, v19, v72
	v_add_u32_e32 v73, v19, v73
	v_add_u32_e32 v74, v19, v74
	v_add_u32_e32 v75, v19, v75
	v_add_u32_e32 v76, v19, v76
	v_add_u32_e32 v77, v19, v77
	v_add_u32_e32 v78, v19, v78
	s_waitcnt vmcnt(0)
	v_cndmask_b32_e32 v11, 0, v134, vcc
	v_cndmask_b32_e32 v12, 0, v135, vcc
	v_cndmask_b32_e32 v13, 0, v136, vcc
	v_cndmask_b32_e32 v14, 0, v137, vcc
	v_cndmask_b32_e32 v15, 0, v138, vcc
	s_branch .LBB0_843
